# rmsnorm row loops: gain vector loaded once before the loop instead of four in-loop loads each followed by vmcnt(0)
# baseline (speedup 1.0000x reference)
; __device__ __forceinline__ void rms_row2(const float* xrow0, const float* xrow1, const float* g, bf16* xo0, bf16* xo1, float* fo0, float* fo1, int lane) {
;     const f32x4* xr0 = (const f32x4*)xrow0 + lane; const f32x4* xr1 = (const f32x4*)xrow1 + lane; const f32x4* gr = (const f32x4*)g + lane;
;     f32x4 v0[4], v1[4]; float s0 = 0.f, s1 = 0.f;
; #pragma unroll
;     for (int j = 0; j < 4; ++j) { v0[j] = xr0[64 * j]; v1[j] = xr1[64 * j]; }
; #pragma unroll
;     for (int j = 0; j < 4; ++j) { s0 += (v0[j].x * v0[j].x + v0[j].y * v0[j].y) + (v0[j].z * v0[j].z + v0[j].w * v0[j].w); s1 += (v1[j].x * v1[j].x + v1[j].y * v1[j].y) + (v1[j].z * v1[j].z + v1[j].w * v1[j].w); }
;     const float r0 = 1.0f / sqrtf(wave_sum(s0, lane) * (1.f / DM) + EPS), r1 = 1.0f / sqrtf(wave_sum(s1, lane) * (1.f / DM) + EPS);
; __global__ void __launch_bounds__(NWAVES * 64, 2) fwd_megakernel(Params P) {
;     ...
;         { const float* xs = (l == 0) ? P.in[0] : X;
;           for (int m = gw; m < MTOK; m += 2 * ngw) { const int m1 = (m + ngw < MTOK) ? m + ngw : m; rms_row2(xs + (size_t)m * DM, xs + (size_t)m1 * DM, P.in[1] + l * DM, XN + (size_t)m * DM, XN + (size_t)m1 * DM, nullptr, nullptr, lno); } }
.LBB0_67:
	v_readlane_b32 s0, v252, 28
	v_readlane_b32 s1, v252, 29
	v_readlane_b32 s14, v254, 31
	s_andn2_b64 vcc, exec, s[0:1]
	v_cndmask_b32_e64 v1, 0, 1, s[0:1]
	v_cmp_ne_u32_e64 s[4:5], 1, v1
	v_readlane_b32 s0, v254, 29
	v_readlane_b32 s15, v254, 32
	v_writelane_b32 v255, s4, 25
	s_mov_b32 s18, 0xf800000
	v_readlane_b32 s1, v254, 30
	v_writelane_b32 v255, s5, 26
	s_cbranch_vccnz .LBB0_70
	v_readlane_b32 s4, v254, 60
	s_mov_b32 s12, s0
	s_and_b64 s[0:1], s[8:9], exec
	v_readlane_b32 s5, v254, 61
	s_cselect_b32 s1, s5, s69
	s_cselect_b32 s0, s4, s68
	v_readlane_b32 s4, v254, 52
	v_readlane_b32 s5, v254, 53
	s_lshl_b32 s26, s4, 10
	v_readlane_b32 s6, v254, 62
	s_lshl_b64 s[4:5], s[26:27], 2
	v_readlane_b32 s7, v254, 63
	s_add_u32 s4, s6, s4
	s_addc_u32 s5, s7, s5
	v_lshlrev_b32_e32 v208, 4, v40
	v_lshl_add_u64 v[30:31], s[4:5], 0, v[208:209]
	v_lshlrev_b32_e32 v1, 2, v40
	v_readlane_b32 s4, v252, 2
	v_xor_b32_e32 v41, 4, v1
	v_xor_b32_e32 v42, 8, v1
	v_xor_b32_e32 v43, 16, v1
	v_xor_b32_e32 v44, 32, v1
	v_xor_b32_e32 v45, 64, v1
	v_xor_b32_e32 v46, 0x80, v1
	v_mov_b32_e32 v1, v209
	v_readlane_b32 s5, v252, 3
	v_lshl_add_u64 v[28:29], s[0:1], 0, v[208:209]
	s_nop 0
	v_lshl_add_u64 v[32:33], s[4:5], 0, v[0:1]
	v_readlane_b32 s4, v254, 25
	v_readlane_b32 s5, v254, 26
	s_nop 1
	v_lshl_add_u64 v[34:35], s[4:5], 0, v[0:1]
	v_readlane_b32 s4, v254, 33
	v_readlane_b32 s5, v254, 34
	s_add_u32 s0, s0, s4
	s_addc_u32 s1, s1, s5
	v_lshl_add_u64 v[36:37], s[0:1], 0, v[208:209]
	v_readlane_b32 s0, v254, 27
	v_readlane_b32 s1, v254, 28
	global_load_dwordx4 v[96:99], v[30:31], off offset:1024
	global_load_dwordx4 v[100:103], v[30:31], off offset:2048
	global_load_dwordx4 v[104:107], v[30:31], off offset:3072
	s_waitcnt vmcnt(0)
.LBB0_69:
	global_load_dwordx4 v[12:15], v[36:37], off
	global_load_dwordx4 v[8:11], v[36:37], off offset:1024
	global_load_dwordx4 v[0:3], v[36:37], off offset:3072
	global_load_dwordx4 v[4:7], v[36:37], off offset:2048
	s_add_i32 s1, s31, s0
	s_cmp_lt_i32 s1, 0x8000
	s_cselect_b32 s4, s1, s0
	s_ashr_i32 s5, s4, 31
	s_lshl_b64 s[6:7], s[4:5], 12
	v_lshl_add_u64 v[20:21], v[28:29], 0, s[6:7]
	global_load_dwordx4 v[24:27], v[30:31], off
	global_load_dwordx4 v[48:51], v[20:21], off
	global_load_dwordx4 v[52:55], v[20:21], off offset:1024
	global_load_dwordx4 v[16:19], v[20:21], off offset:3072
	s_nop 0
	global_load_dwordx4 v[20:23], v[20:21], off offset:2048
	s_lshl_b64 s[4:5], s[4:5], 11
	v_lshl_add_u64 v[38:39], v[32:33], 0, s[4:5]
	s_add_i32 s0, s0, s12
	v_lshl_add_u64 v[36:37], v[36:37], 0, s[14:15]
	s_cmpk_gt_i32 s0, 0x7fff
	s_waitcnt vmcnt(8)
	v_pk_mul_f32 v[56:57], v[14:15], v[14:15]
	v_pk_mul_f32 v[58:59], v[12:13], v[12:13]
	s_waitcnt vmcnt(7)
	v_pk_mul_f32 v[60:61], v[10:11], v[10:11]
	v_pk_mul_f32 v[62:63], v[8:9], v[8:9]
	v_pk_mov_b32 v[68:69], v[58:59], v[56:57] op_sel:[1,0]
	v_mov_b32_e32 v59, v57
	v_pk_mov_b32 v[56:57], v[62:63], v[60:61] op_sel:[1,0]
	v_mov_b32_e32 v63, v61
	s_waitcnt vmcnt(6)
	v_mul_f32_e32 v67, v1, v1
	s_waitcnt vmcnt(5)
	v_mul_f32_e32 v64, v5, v5
	v_mul_f32_e32 v66, v7, v7
	v_pk_add_f32 v[58:59], v[68:69], v[58:59]
	v_pk_add_f32 v[56:57], v[56:57], v[62:63]
	v_mul_f32_e32 v47, v0, v0
	v_mul_f32_e32 v70, v2, v2
	v_mul_f32_e32 v71, v3, v3
	v_pk_fma_f32 v[60:61], v[4:5], v[4:5], v[64:65] op_sel_hi:[1,1,0]
	v_pk_fma_f32 v[64:65], v[6:7], v[6:7], v[66:67] op_sel_hi:[1,1,0]
	v_pk_add_f32 v[58:59], v[58:59], v[58:59] op_sel:[0,1] op_sel_hi:[1,0]
	v_pk_add_f32 v[56:57], v[56:57], v[56:57] op_sel:[0,1] op_sel_hi:[1,0]
	v_mov_b32_e32 v61, v70
	v_mov_b32_e32 v65, v71
	v_mov_b32_e32 v59, v47
	v_mov_b32_e32 v57, v67
	v_pk_add_f32 v[60:61], v[60:61], v[64:65]
	v_pk_add_f32 v[56:57], v[58:59], v[56:57]
	s_waitcnt vmcnt(3)
	v_pk_mul_f32 v[58:59], v[50:51], v[50:51]
	v_pk_mul_f32 v[62:63], v[48:49], v[48:49]
	s_waitcnt vmcnt(2)
	v_pk_mul_f32 v[64:65], v[54:55], v[54:55]
	v_pk_mul_f32 v[66:67], v[52:53], v[52:53]
	v_pk_add_f32 v[56:57], v[56:57], v[60:61]
	v_pk_mov_b32 v[70:71], v[62:63], v[58:59] op_sel:[1,0]
	v_mov_b32_e32 v63, v59
	v_pk_mov_b32 v[58:59], v[66:67], v[64:65] op_sel:[1,0]
	v_mov_b32_e32 v67, v65
	v_add_f32_e32 v64, v56, v57
	s_waitcnt vmcnt(1)
	v_mul_f32_e32 v69, v17, v17
	s_waitcnt vmcnt(0)
	v_mul_f32_e32 v60, v21, v21
	v_mul_f32_e32 v68, v23, v23
	v_pk_add_f32 v[62:63], v[70:71], v[62:63]
	v_pk_add_f32 v[58:59], v[58:59], v[66:67]
	ds_bpermute_b32 v65, v41, v64
	v_mul_f32_e32 v47, v16, v16
	v_mul_f32_e32 v72, v18, v18
	v_mul_f32_e32 v73, v19, v19
	v_pk_fma_f32 v[56:57], v[20:21], v[20:21], v[60:61] op_sel_hi:[1,1,0]
	v_pk_fma_f32 v[60:61], v[22:23], v[22:23], v[68:69] op_sel_hi:[1,1,0]
	v_pk_add_f32 v[62:63], v[62:63], v[62:63] op_sel:[0,1] op_sel_hi:[1,0]
	v_pk_add_f32 v[58:59], v[58:59], v[58:59] op_sel:[0,1] op_sel_hi:[1,0]
	v_mov_b32_e32 v57, v72
	v_mov_b32_e32 v61, v73
	v_mov_b32_e32 v63, v47
	v_mov_b32_e32 v59, v69
	v_pk_add_f32 v[56:57], v[56:57], v[60:61]
	v_pk_add_f32 v[58:59], v[62:63], v[58:59]
	s_nop 0
	v_pk_add_f32 v[56:57], v[58:59], v[56:57]
	s_nop 0
	v_add_f32_e32 v47, v56, v57
	s_waitcnt lgkmcnt(0)
	v_add_f32_e32 v56, v64, v65
	ds_bpermute_b32 v57, v42, v56
	ds_bpermute_b32 v58, v41, v47
	s_waitcnt lgkmcnt(1)
	v_add_f32_e32 v56, v56, v57
	s_waitcnt lgkmcnt(0)
	v_add_f32_e32 v47, v47, v58
	ds_bpermute_b32 v57, v43, v56
	ds_bpermute_b32 v58, v42, v47
	s_waitcnt lgkmcnt(1)
	v_add_f32_e32 v56, v56, v57
	s_waitcnt lgkmcnt(0)
	v_add_f32_e32 v47, v47, v58
	ds_bpermute_b32 v57, v44, v56
	ds_bpermute_b32 v58, v43, v47
	s_waitcnt lgkmcnt(1)
	v_add_f32_e32 v56, v56, v57
	s_waitcnt lgkmcnt(0)
	v_add_f32_e32 v47, v47, v58
	ds_bpermute_b32 v57, v45, v56
	ds_bpermute_b32 v58, v44, v47
	s_waitcnt lgkmcnt(1)
; __device__ __forceinline__ float wave_sum(float v, int lane) {
; #pragma unroll
;     for (int o = 1; o < 64; o <<= 1) v += __builtin_bit_cast(float, __builtin_amdgcn_ds_bpermute((lane ^ o) << 2, __builtin_bit_cast(int, v)));
;     return v;
; __device__ __forceinline__ void rms_row2(const float* xrow0, const float* xrow1, const float* g, bf16* xo0, bf16* xo1, float* fo0, float* fo1, int lane) {
;     ...
;     const float r0 = 1.0f / sqrtf(wave_sum(s0, lane) * (1.f / DM) + EPS), r1 = 1.0f / sqrtf(wave_sum(s1, lane) * (1.f / DM) + EPS);
	v_add_f32_e32 v56, v56, v57
	s_waitcnt lgkmcnt(0)
	v_add_f32_e32 v47, v47, v58
	ds_bpermute_b32 v57, v46, v56
	ds_bpermute_b32 v58, v45, v47
	s_waitcnt lgkmcnt(1)
	v_add_f32_e32 v56, v56, v57
	s_waitcnt lgkmcnt(0)
	v_add_f32_e32 v47, v47, v58
	v_fmamk_f32 v56, v56, 0x3a800000, v240
	ds_bpermute_b32 v57, v46, v47
	v_mul_f32_e32 v58, 0x4f800000, v56
	v_cmp_gt_f32_e32 vcc, s18, v56
	s_waitcnt lgkmcnt(0)
; __device__ __forceinline__ unsigned pk2(float lo, float hi) { return f2bf(lo) | (f2bf(hi) << 16); }
; __device__ __forceinline__ void rms_row2(const float* xrow0, const float* xrow1, const float* g, bf16* xo0, bf16* xo1, float* fo0, float* fo1, int lane) {
;     ...
;     const float r0 = 1.0f / sqrtf(wave_sum(s0, lane) * (1.f / DM) + EPS), r1 = 1.0f / sqrtf(wave_sum(s1, lane) * (1.f / DM) + EPS);
; #pragma unroll
;     for (int j = 0; j < 4; ++j) { const f32x4 gg = gr[64 * j]; const f32x4 y0 = v0[j] * r0 * gg, y1 = v1[j] * r1 * gg;
;         if (xo0) { ((unsigned long long*)xo0)[lane + 64 * j] = (unsigned long long)pk2(y0.x, y0.y) | ((unsigned long long)pk2(y0.z, y0.w) << 32);
;                    ((unsigned long long*)xo1)[lane + 64 * j] = (unsigned long long)pk2(y1.x, y1.y) | ((unsigned long long)pk2(y1.z, y1.w) << 32); }
;         else { ((f32x4*)fo0)[lane + 64 * j] = y0; ((f32x4*)fo1)[lane + 64 * j] = y1; } }
	v_add_f32_e32 v47, v47, v57
	v_cndmask_b32_e32 v56, v56, v58, vcc
	v_sqrt_f32_e32 v58, v56
	v_fmamk_f32 v47, v47, 0x3a800000, v240
	v_mul_f32_e32 v60, 0x4f800000, v47
	v_cmp_gt_f32_e64 s[4:5], s18, v47
	v_add_u32_e32 v57, -1, v58
	v_add_u32_e32 v59, 1, v58
	v_fma_f32 v61, -v57, v58, v56
	v_fma_f32 v62, -v59, v58, v56
	v_cndmask_b32_e64 v47, v47, v60, s[4:5]
	v_cmp_ge_f32_e64 s[6:7], 0, v61
	s_nop 1
	v_cndmask_b32_e64 v57, v58, v57, s[6:7]
	v_sqrt_f32_e32 v58, v47
	v_cmp_lt_f32_e64 s[6:7], 0, v62
	s_nop 1
	v_cndmask_b32_e64 v57, v57, v59, s[6:7]
	v_mul_f32_e32 v59, 0x37800000, v57
	v_cndmask_b32_e32 v57, v57, v59, vcc
	v_cmp_class_f32_e32 vcc, v56, v244
	v_add_u32_e32 v59, 1, v58
	v_fma_f32 v63, -v59, v58, v47
	v_cndmask_b32_e32 v56, v57, v56, vcc
	v_add_u32_e32 v57, -1, v58
	v_div_scale_f32 v60, s[6:7], v56, v56, 1.0
	v_fma_f32 v62, -v57, v58, v47
	v_cmp_ge_f32_e64 s[6:7], 0, v62
	v_rcp_f32_e32 v64, v60
	v_div_scale_f32 v61, vcc, 1.0, v56, 1.0
	v_cndmask_b32_e64 v57, v58, v57, s[6:7]
	v_cmp_lt_f32_e64 s[6:7], 0, v63
	s_nop 1
	v_cndmask_b32_e64 v57, v57, v59, s[6:7]
	v_mul_f32_e32 v58, 0x37800000, v57
	v_cndmask_b32_e64 v57, v57, v58, s[4:5]
	v_cmp_class_f32_e64 s[4:5], v47, v244
	v_fma_f32 v58, -v60, v64, 1.0
	v_fmac_f32_e32 v64, v58, v64
	v_cndmask_b32_e64 v47, v57, v47, s[4:5]
	v_div_scale_f32 v57, s[4:5], v47, v47, 1.0
	v_mul_f32_e32 v59, v61, v64
	v_rcp_f32_e32 v62, v57
	v_fma_f32 v63, -v60, v59, v61
	v_fmac_f32_e32 v59, v63, v64
	v_fma_f32 v60, -v60, v59, v61
	v_div_fmas_f32 v59, v60, v64, v59
	v_fma_f32 v60, -v57, v62, 1.0
	v_div_scale_f32 v58, s[4:5], 1.0, v47, 1.0
	v_fmac_f32_e32 v62, v60, v62
	v_div_fixup_f32 v56, v59, v56, 1.0
	v_mul_f32_e32 v59, v58, v62
	v_pk_mul_f32 v[12:13], v[12:13], v[56:57] op_sel_hi:[1,0]
	v_pk_mul_f32 v[14:15], v[14:15], v[56:57] op_sel_hi:[1,0]
	v_fma_f32 v60, -v57, v59, v58
	v_pk_mul_f32 v[14:15], v[26:27], v[14:15]
	v_pk_mul_f32 v[12:13], v[24:25], v[12:13]
	v_fmac_f32_e32 v59, v60, v62
	v_bfe_u32 v60, v12, 16, 1
	v_bfe_u32 v63, v14, 16, 1
	v_fma_f32 v57, -v57, v59, v58
	s_mov_b64 vcc, s[4:5]
	v_bfe_u32 v61, v13, 16, 1
	v_bfe_u32 v64, v15, 16, 1
	v_add3_u32 v12, v12, v60, s33
	v_add3_u32 v14, v14, v63, s33
	v_div_fmas_f32 v57, v57, v62, v59
	v_add3_u32 v13, v13, v61, s33
	v_add3_u32 v15, v15, v64, s33
	v_lshrrev_b32_e32 v12, 16, v12
	v_lshrrev_b32_e32 v14, 16, v14
	v_div_fixup_f32 v58, v57, v47, 1.0
	v_and_or_b32 v12, v13, s37, v12
	v_and_or_b32 v13, v15, s37, v14
	v_pk_mul_f32 v[14:15], v[48:49], v[58:59] op_sel_hi:[1,0]
	v_pk_mul_f32 v[48:49], v[50:51], v[58:59] op_sel_hi:[1,0]
	global_store_dwordx2 v[34:35], v[12:13], off
	v_pk_mul_f32 v[12:13], v[26:27], v[48:49]
	v_pk_mul_f32 v[14:15], v[24:25], v[14:15]
	v_bfe_u32 v26, v12, 16, 1
	v_bfe_u32 v24, v14, 16, 1
	v_bfe_u32 v25, v15, 16, 1
	v_bfe_u32 v27, v13, 16, 1
	v_add3_u32 v14, v14, v24, s33
	v_add3_u32 v12, v12, v26, s33
	v_add3_u32 v15, v15, v25, s33
	v_add3_u32 v13, v13, v27, s33
	v_lshrrev_b32_e32 v14, 16, v14
	v_lshrrev_b32_e32 v24, 16, v12
	v_and_or_b32 v12, v15, s37, v14
	v_and_or_b32 v13, v13, s37, v24
	global_store_dwordx2 v[38:39], v[12:13], off
	v_mov_b64_e32 v[12:13], v[96:97]
	v_mov_b64_e32 v[14:15], v[98:99]
	v_pk_mul_f32 v[8:9], v[8:9], v[56:57] op_sel_hi:[1,0]
	v_pk_mul_f32 v[10:11], v[10:11], v[56:57] op_sel_hi:[1,0]
	v_pk_mul_f32 v[24:25], v[52:53], v[58:59] op_sel_hi:[1,0]
	v_pk_mul_f32 v[26:27], v[54:55], v[58:59] op_sel_hi:[1,0]
	v_pk_mul_f32 v[4:5], v[4:5], v[56:57] op_sel_hi:[1,0]
	v_pk_mul_f32 v[6:7], v[6:7], v[56:57] op_sel_hi:[1,0]
	v_pk_mul_f32 v[0:1], v[0:1], v[56:57] op_sel_hi:[1,0]
	v_pk_mul_f32 v[2:3], v[2:3], v[56:57] op_sel_hi:[1,0]
	v_pk_mul_f32 v[10:11], v[14:15], v[10:11]
	v_pk_mul_f32 v[8:9], v[12:13], v[8:9]
	v_pk_mul_f32 v[14:15], v[14:15], v[26:27]
	v_pk_mul_f32 v[12:13], v[12:13], v[24:25]
	v_bfe_u32 v24, v8, 16, 1
	v_bfe_u32 v26, v10, 16, 1
	v_bfe_u32 v25, v9, 16, 1
	v_bfe_u32 v27, v11, 16, 1
	v_bfe_u32 v47, v12, 16, 1
	v_bfe_u32 v49, v14, 16, 1
	v_add3_u32 v8, v8, v24, s33
	v_add3_u32 v10, v10, v26, s33
	v_bfe_u32 v48, v13, 16, 1
	v_bfe_u32 v50, v15, 16, 1
	v_add3_u32 v9, v9, v25, s33
	v_add3_u32 v11, v11, v27, s33
	v_add3_u32 v12, v12, v47, s33
	v_add3_u32 v14, v14, v49, s33
	v_lshrrev_b32_e32 v8, 16, v8
	v_lshrrev_b32_e32 v10, 16, v10
	v_add3_u32 v13, v13, v48, s33
	v_add3_u32 v15, v15, v50, s33
	v_lshrrev_b32_e32 v12, 16, v12
	v_lshrrev_b32_e32 v14, 16, v14
	v_and_or_b32 v8, v9, s37, v8
	v_and_or_b32 v9, v11, s37, v10
	v_and_or_b32 v10, v13, s37, v12
	v_and_or_b32 v11, v15, s37, v14
	global_store_dwordx2 v[34:35], v[8:9], off offset:512
	global_store_dwordx2 v[38:39], v[10:11], off offset:512
	v_mov_b64_e32 v[8:9], v[100:101]
	v_mov_b64_e32 v[10:11], v[102:103]
	v_pk_mul_f32 v[12:13], v[20:21], v[58:59] op_sel_hi:[1,0]
	v_pk_mul_f32 v[14:15], v[22:23], v[58:59] op_sel_hi:[1,0]
	v_pk_mul_f32 v[6:7], v[6:7], v[10:11]
	v_pk_mul_f32 v[4:5], v[4:5], v[8:9]
	v_pk_mul_f32 v[10:11], v[10:11], v[14:15]
	v_pk_mul_f32 v[8:9], v[8:9], v[12:13]
	v_bfe_u32 v12, v4, 16, 1
	v_bfe_u32 v14, v6, 16, 1
	v_bfe_u32 v13, v5, 16, 1
	v_bfe_u32 v15, v7, 16, 1
	v_bfe_u32 v20, v8, 16, 1
	v_bfe_u32 v22, v10, 16, 1
	v_add3_u32 v4, v4, v12, s33
	v_add3_u32 v6, v6, v14, s33
	v_bfe_u32 v21, v9, 16, 1
	v_bfe_u32 v23, v11, 16, 1
	v_add3_u32 v5, v5, v13, s33
	v_add3_u32 v7, v7, v15, s33
	v_add3_u32 v8, v8, v20, s33
	v_add3_u32 v10, v10, v22, s33
	v_lshrrev_b32_e32 v4, 16, v4
	v_lshrrev_b32_e32 v6, 16, v6
	v_add3_u32 v9, v9, v21, s33
	v_add3_u32 v11, v11, v23, s33
	v_lshrrev_b32_e32 v8, 16, v8
	v_lshrrev_b32_e32 v10, 16, v10
	v_and_or_b32 v4, v5, s37, v4
	v_and_or_b32 v5, v7, s37, v6
	v_and_or_b32 v6, v9, s37, v8
	v_and_or_b32 v7, v11, s37, v10
	global_store_dwordx2 v[34:35], v[4:5], off offset:1024
	global_store_dwordx2 v[38:39], v[6:7], off offset:1024
	v_mov_b64_e32 v[4:5], v[104:105]
	v_mov_b64_e32 v[6:7], v[106:107]
	v_pk_mul_f32 v[8:9], v[16:17], v[58:59] op_sel_hi:[1,0]
	v_pk_mul_f32 v[10:11], v[18:19], v[58:59] op_sel_hi:[1,0]
	v_pk_mul_f32 v[2:3], v[2:3], v[6:7]
	v_pk_mul_f32 v[0:1], v[0:1], v[4:5]
	v_pk_mul_f32 v[6:7], v[10:11], v[6:7]
	v_pk_mul_f32 v[4:5], v[8:9], v[4:5]
	v_bfe_u32 v8, v0, 16, 1
	v_bfe_u32 v10, v2, 16, 1
	v_bfe_u32 v9, v1, 16, 1
	v_bfe_u32 v11, v3, 16, 1
	v_bfe_u32 v12, v4, 16, 1
	v_bfe_u32 v14, v6, 16, 1
	v_add3_u32 v0, v0, v8, s33
	v_add3_u32 v2, v2, v10, s33
	v_bfe_u32 v13, v5, 16, 1
	v_bfe_u32 v15, v7, 16, 1
	v_add3_u32 v1, v1, v9, s33
	v_add3_u32 v3, v3, v11, s33
	v_add3_u32 v4, v4, v12, s33
	v_add3_u32 v6, v6, v14, s33
	v_lshrrev_b32_e32 v0, 16, v0
	v_lshrrev_b32_e32 v2, 16, v2
	v_add3_u32 v5, v5, v13, s33
	v_add3_u32 v7, v7, v15, s33
	v_lshrrev_b32_e32 v4, 16, v4
	v_lshrrev_b32_e32 v6, 16, v6
	v_and_or_b32 v0, v1, s37, v0
	v_and_or_b32 v1, v3, s37, v2
	v_and_or_b32 v2, v5, s37, v4
	v_and_or_b32 v3, v7, s37, v6
	global_store_dwordx2 v[34:35], v[0:1], off offset:1536
	global_store_dwordx2 v[38:39], v[2:3], off offset:1536
	v_lshl_add_u64 v[34:35], v[34:35], 0, s[34:35]
	s_cbranch_scc0 .LBB0_69

; #define OPQV(v) asm volatile("" : "+v"(v) :: "memory")
; __device__ __forceinline__ void rms_row2(const float* xrow0, const float* xrow1, const float* g, bf16* xo0, bf16* xo1, float* fo0, float* fo1, int lane) {
;     const f32x4* xr0 = (const f32x4*)xrow0 + lane; const f32x4* xr1 = (const f32x4*)xrow1 + lane; const f32x4* gr = (const f32x4*)g + lane;
;     f32x4 v0[4], v1[4]; float s0 = 0.f, s1 = 0.f;
; #pragma unroll
;     for (int j = 0; j < 4; ++j) { v0[j] = xr0[64 * j]; v1[j] = xr1[64 * j]; }
; #pragma unroll
;     for (int j = 0; j < 4; ++j) { s0 += (v0[j].x * v0[j].x + v0[j].y * v0[j].y) + (v0[j].z * v0[j].z + v0[j].w * v0[j].w); s1 += (v1[j].x * v1[j].x + v1[j].y * v1[j].y) + (v1[j].z * v1[j].z + v1[j].w * v1[j].w); }
;     const float r0 = 1.0f / sqrtf(wave_sum(s0, lane) * (1.f / DM) + EPS), r1 = 1.0f / sqrtf(wave_sum(s1, lane) * (1.f / DM) + EPS);
; __global__ void __launch_bounds__(NWAVES * 64, 2) fwd_megakernel(Params P) {
;     ...
;         lno = (int)threadIdx.x; OPQV(lno); lno &= 63; for (int m = gw; m < MTOK; m += 2 * ngw) { const int m1 = (m + ngw < MTOK) ? m + ngw : m; rms_row2(X + (size_t)m * DM, X + (size_t)m1 * DM, P.in[5] + l * DM, XN + (size_t)m * DM, XN + (size_t)m1 * DM, nullptr, nullptr, lno); }
.LBB0_274:
	s_or_b64 exec, exec, s[0:1]
	s_waitcnt lgkmcnt(0)
	v_mov_b32_e32 v0, v236
	s_barrier
	v_readlane_b32 s0, v255, 25
	v_readlane_b32 s1, v255, 26
	v_readlane_b32 s14, v254, 31
	s_and_b64 vcc, exec, s[0:1]
	v_readlane_b32 s8, v254, 29
	v_readlane_b32 s15, v254, 32
	s_mov_b32 s7, 0xf800000
	v_readlane_b32 s9, v254, 30
	s_cbranch_vccnz .LBB0_277
	v_readlane_b32 s0, v254, 52
	v_readlane_b32 s1, v254, 53
	s_lshl_b32 s26, s0, 10
	s_lshl_b64 s[0:1], s[26:27], 2
	v_readlane_b32 s40, v255, 0
	v_and_b32_e32 v0, 63, v0
	v_readlane_b32 s41, v255, 1
	s_add_u32 s0, s40, s0
	s_addc_u32 s1, s41, s1
	v_lshlrev_b32_e32 v208, 4, v0
	v_lshl_add_u64 v[34:35], s[0:1], 0, v[208:209]
	v_lshlrev_b32_e32 v1, 2, v0
	v_readlane_b32 s0, v252, 2
	v_xor_b32_e32 v43, 4, v1
	v_xor_b32_e32 v45, 8, v1
	v_xor_b32_e32 v46, 16, v1
	v_xor_b32_e32 v47, 32, v1
	v_xor_b32_e32 v48, 64, v1
	v_xor_b32_e32 v49, 0x80, v1
	v_lshlrev_b32_e32 v0, 3, v0
	v_mov_b32_e32 v1, v209
	v_readlane_b32 s1, v252, 3
	v_lshl_add_u64 v[32:33], s[68:69], 0, v[208:209]
	v_readlane_b32 s42, v255, 2
	v_lshl_add_u64 v[36:37], s[0:1], 0, v[0:1]
	v_readlane_b32 s0, v254, 25
	v_readlane_b32 s1, v254, 26
	v_readlane_b32 s43, v255, 3
	v_readlane_b32 s44, v255, 4
	v_lshl_add_u64 v[38:39], s[0:1], 0, v[0:1]
	v_readlane_b32 s0, v254, 35
	v_readlane_b32 s1, v254, 36
	v_readlane_b32 s45, v255, 5
	v_readlane_b32 s46, v255, 6
	v_lshl_add_u64 v[40:41], s[0:1], 0, v[208:209]
	v_readlane_b32 s0, v254, 27
	s_mov_b32 s6, s0
	v_readlane_b32 s47, v255, 7
	v_readlane_b32 s48, v255, 8
	v_readlane_b32 s49, v255, 9
	v_readlane_b32 s50, v255, 10
	v_readlane_b32 s51, v255, 11
	v_readlane_b32 s52, v255, 12
	v_readlane_b32 s53, v255, 13
	v_readlane_b32 s54, v255, 14
	v_readlane_b32 s55, v255, 15
	v_readlane_b32 s1, v254, 28
	global_load_dwordx4 v[96:99], v[34:35], off
	global_load_dwordx4 v[100:103], v[34:35], off offset:1024
	global_load_dwordx4 v[104:107], v[34:35], off offset:2048
	global_load_dwordx4 v[108:111], v[34:35], off offset:3072
	s_waitcnt vmcnt(0)
.LBB0_276:
	s_add_i32 s0, s31, s6
	s_cmp_lt_i32 s0, 0x8000
	s_cselect_b32 s0, s0, s6
	s_ashr_i32 s1, s0, 31
	s_lshl_b64 s[4:5], s[0:1], 12
	v_lshl_add_u64 v[0:1], v[32:33], 0, s[4:5]
	global_load_dwordx4 v[28:31], v[40:41], off
	global_load_dwordx4 v[24:27], v[0:1], off
	global_load_dwordx4 v[20:23], v[40:41], off offset:1024
	global_load_dwordx4 v[16:19], v[0:1], off offset:1024
	global_load_dwordx4 v[12:15], v[40:41], off offset:2048
	global_load_dwordx4 v[8:11], v[0:1], off offset:2048
	global_load_dwordx4 v[4:7], v[40:41], off offset:3072
	s_nop 0
	global_load_dwordx4 v[0:3], v[0:1], off offset:3072
	s_lshl_b64 s[0:1], s[0:1], 11
	s_add_i32 s6, s6, s8
	v_lshl_add_u64 v[40:41], v[40:41], 0, s[14:15]
	s_cmpk_gt_i32 s6, 0x7fff
	s_waitcnt vmcnt(7)
	v_pk_mul_f32 v[50:51], v[30:31], v[30:31]
	v_pk_mul_f32 v[52:53], v[28:29], v[28:29]
	s_waitcnt vmcnt(1)
	v_mul_f32_e32 v42, v4, v4
	v_pk_mov_b32 v[54:55], v[52:53], v[50:51] op_sel:[1,0]
	v_mov_b32_e32 v53, v51
	v_pk_add_f32 v[50:51], v[54:55], v[52:53]
	v_pk_mul_f32 v[52:53], v[26:27], v[26:27]
	v_pk_mul_f32 v[54:55], v[24:25], v[24:25]
	v_mul_f32_e32 v44, v5, v5
	v_pk_mov_b32 v[56:57], v[54:55], v[52:53] op_sel:[1,0]
	v_mov_b32_e32 v55, v53
	v_pk_add_f32 v[52:53], v[56:57], v[54:55]
	v_pk_mul_f32 v[54:55], v[22:23], v[22:23]
	v_pk_mul_f32 v[56:57], v[20:21], v[20:21]
	v_pk_add_f32 v[50:51], v[50:51], v[50:51] op_sel:[0,1] op_sel_hi:[1,0]
	v_pk_mov_b32 v[58:59], v[56:57], v[54:55] op_sel:[1,0]
	v_mov_b32_e32 v57, v55
	v_pk_add_f32 v[54:55], v[58:59], v[56:57]
	v_pk_mul_f32 v[56:57], v[18:19], v[18:19]
	v_pk_mul_f32 v[58:59], v[16:17], v[16:17]
	v_pk_add_f32 v[54:55], v[54:55], v[54:55] op_sel:[0,1] op_sel_hi:[1,0]
	v_pk_mov_b32 v[60:61], v[58:59], v[56:57] op_sel:[1,0]
	v_mov_b32_e32 v59, v57
	v_mov_b32_e32 v51, v42
	v_mov_b32_e32 v55, v44
	v_mul_f32_e32 v42, v13, v13
	v_pk_add_f32 v[56:57], v[60:61], v[58:59]
	v_mul_f32_e32 v58, v6, v6
	v_pk_add_f32 v[50:51], v[50:51], v[54:55]
	v_pk_fma_f32 v[54:55], v[12:13], v[12:13], v[42:43] op_sel_hi:[1,1,0]
	v_mul_f32_e32 v42, v15, v15
	v_mul_f32_e32 v60, v7, v7
	v_mov_b32_e32 v55, v58
	v_pk_fma_f32 v[58:59], v[14:15], v[14:15], v[42:43] op_sel_hi:[1,1,0]
	s_waitcnt vmcnt(0)
	v_mul_f32_e32 v42, v0, v0
	v_mov_b32_e32 v59, v60
	v_pk_add_f32 v[54:55], v[54:55], v[58:59]
	v_mul_f32_e32 v58, v3, v3
	v_pk_add_f32 v[50:51], v[50:51], v[54:55]
	v_mul_f32_e32 v54, v1, v1
	v_add_f32_e32 v44, v50, v51
	v_pk_add_f32 v[50:51], v[52:53], v[52:53] op_sel:[0,1] op_sel_hi:[1,0]
	v_pk_add_f32 v[52:53], v[56:57], v[56:57] op_sel:[0,1] op_sel_hi:[1,0]
	v_mov_b32_e32 v51, v42
	v_mov_b32_e32 v53, v54
	v_mul_f32_e32 v42, v9, v9
	v_mul_f32_e32 v55, v2, v2
	v_pk_add_f32 v[50:51], v[50:51], v[52:53]
	v_pk_fma_f32 v[52:53], v[8:9], v[8:9], v[42:43] op_sel_hi:[1,1,0]
	v_mul_f32_e32 v42, v11, v11
	v_mov_b32_e32 v53, v55
	v_pk_fma_f32 v[54:55], v[10:11], v[10:11], v[42:43] op_sel_hi:[1,1,0]
	ds_bpermute_b32 v42, v43, v44
	v_mov_b32_e32 v55, v58
	v_pk_add_f32 v[52:53], v[52:53], v[54:55]
	s_waitcnt lgkmcnt(0)
	v_add_f32_e32 v42, v44, v42
	ds_bpermute_b32 v44, v45, v42
	v_pk_add_f32 v[50:51], v[50:51], v[52:53]
	s_waitcnt lgkmcnt(0)
	v_add_f32_e32 v42, v42, v44
	ds_bpermute_b32 v44, v46, v42
	v_add_f32_e32 v50, v50, v51
	s_waitcnt lgkmcnt(0)
	v_add_f32_e32 v42, v42, v44
	ds_bpermute_b32 v44, v47, v42
	s_waitcnt lgkmcnt(0)
	v_add_f32_e32 v42, v42, v44
	ds_bpermute_b32 v44, v48, v42
	s_waitcnt lgkmcnt(0)
	v_add_f32_e32 v42, v42, v44
	ds_bpermute_b32 v44, v49, v42
	s_waitcnt lgkmcnt(0)
; __device__ __forceinline__ void rms_row2(const float* xrow0, const float* xrow1, const float* g, bf16* xo0, bf16* xo1, float* fo0, float* fo1, int lane) {
;     ...
;     const float r0 = 1.0f / sqrtf(wave_sum(s0, lane) * (1.f / DM) + EPS), r1 = 1.0f / sqrtf(wave_sum(s1, lane) * (1.f / DM) + EPS);
; #pragma unroll
;     for (int j = 0; j < 4; ++j) { const f32x4 gg = gr[64 * j]; const f32x4 y0 = v0[j] * r0 * gg, y1 = v1[j] * r1 * gg;
	v_add_f32_e32 v42, v42, v44
	v_fmamk_f32 v42, v42, 0x3a800000, v240
	v_cmp_gt_f32_e32 vcc, s7, v42
	v_mul_f32_e32 v44, 0x4f800000, v42
	s_nop 0
	v_cndmask_b32_e32 v42, v42, v44, vcc
	v_sqrt_f32_e32 v44, v42
	s_nop 0
	v_add_u32_e32 v51, -1, v44
	v_fma_f32 v52, -v51, v44, v42
	v_cmp_ge_f32_e64 s[4:5], 0, v52
	v_add_u32_e32 v52, 1, v44
	s_nop 0
	v_cndmask_b32_e64 v51, v44, v51, s[4:5]
	v_fma_f32 v44, -v52, v44, v42
	v_cmp_lt_f32_e64 s[4:5], 0, v44
	s_nop 1
	v_cndmask_b32_e64 v44, v51, v52, s[4:5]
	v_mul_f32_e32 v51, 0x37800000, v44
	v_cndmask_b32_e32 v44, v44, v51, vcc
	v_cmp_class_f32_e32 vcc, v42, v244
	s_nop 1
	v_cndmask_b32_e32 v42, v44, v42, vcc
	v_div_scale_f32 v44, s[4:5], v42, v42, 1.0
	v_rcp_f32_e32 v51, v44
	s_nop 0
	v_fma_f32 v52, -v44, v51, 1.0
	v_fmac_f32_e32 v51, v52, v51
	v_div_scale_f32 v52, vcc, 1.0, v42, 1.0
	v_mul_f32_e32 v53, v52, v51
	v_fma_f32 v54, -v44, v53, v52
	v_fmac_f32_e32 v53, v54, v51
	v_fma_f32 v44, -v44, v53, v52
	v_div_fmas_f32 v44, v44, v51, v53
	v_div_fixup_f32 v42, v44, v42, 1.0
	ds_bpermute_b32 v44, v43, v50
	v_pk_mul_f32 v[28:29], v[28:29], v[42:43] op_sel_hi:[1,0]
	v_pk_mul_f32 v[30:31], v[30:31], v[42:43] op_sel_hi:[1,0]
	v_pk_mul_f32 v[20:21], v[20:21], v[42:43] op_sel_hi:[1,0]
	v_pk_mul_f32 v[22:23], v[22:23], v[42:43] op_sel_hi:[1,0]
	s_waitcnt lgkmcnt(0)
	v_add_f32_e32 v44, v50, v44
	ds_bpermute_b32 v50, v45, v44
	v_pk_mul_f32 v[12:13], v[12:13], v[42:43] op_sel_hi:[1,0]
	v_pk_mul_f32 v[14:15], v[14:15], v[42:43] op_sel_hi:[1,0]
	v_pk_mul_f32 v[4:5], v[4:5], v[42:43] op_sel_hi:[1,0]
	v_pk_mul_f32 v[6:7], v[6:7], v[42:43] op_sel_hi:[1,0]
	s_waitcnt lgkmcnt(0)
	v_add_f32_e32 v44, v44, v50
	ds_bpermute_b32 v50, v46, v44
	s_waitcnt lgkmcnt(0)
	v_add_f32_e32 v44, v44, v50
	ds_bpermute_b32 v50, v47, v44
	s_waitcnt lgkmcnt(0)
	v_add_f32_e32 v44, v44, v50
	ds_bpermute_b32 v50, v48, v44
	s_waitcnt lgkmcnt(0)
	v_add_f32_e32 v44, v44, v50
	ds_bpermute_b32 v50, v49, v44
	s_waitcnt lgkmcnt(0)
; __device__ __forceinline__ unsigned pk2(float lo, float hi) { return f2bf(lo) | (f2bf(hi) << 16); }
; __device__ __forceinline__ void rms_row2(const float* xrow0, const float* xrow1, const float* g, bf16* xo0, bf16* xo1, float* fo0, float* fo1, int lane) {
;     ...
;     const float r0 = 1.0f / sqrtf(wave_sum(s0, lane) * (1.f / DM) + EPS), r1 = 1.0f / sqrtf(wave_sum(s1, lane) * (1.f / DM) + EPS);
; #pragma unroll
;     for (int j = 0; j < 4; ++j) { const f32x4 gg = gr[64 * j]; const f32x4 y0 = v0[j] * r0 * gg, y1 = v1[j] * r1 * gg;
;         if (xo0) { ((unsigned long long*)xo0)[lane + 64 * j] = (unsigned long long)pk2(y0.x, y0.y) | ((unsigned long long)pk2(y0.z, y0.w) << 32);
;                    ((unsigned long long*)xo1)[lane + 64 * j] = (unsigned long long)pk2(y1.x, y1.y) | ((unsigned long long)pk2(y1.z, y1.w) << 32); }
;         else { ((f32x4*)fo0)[lane + 64 * j] = y0; ((f32x4*)fo1)[lane + 64 * j] = y1; } }
	v_add_f32_e32 v44, v44, v50
	v_fmamk_f32 v44, v44, 0x3a800000, v240
	v_cmp_gt_f32_e32 vcc, s7, v44
	v_mul_f32_e32 v50, 0x4f800000, v44
	s_nop 0
	v_cndmask_b32_e32 v44, v44, v50, vcc
	v_sqrt_f32_e32 v50, v44
	s_nop 0
	v_add_u32_e32 v51, -1, v50
	v_fma_f32 v52, -v51, v50, v44
	v_cmp_ge_f32_e64 s[4:5], 0, v52
	v_add_u32_e32 v52, 1, v50
	s_nop 0
	v_cndmask_b32_e64 v51, v50, v51, s[4:5]
	v_fma_f32 v50, -v52, v50, v44
	v_cmp_lt_f32_e64 s[4:5], 0, v50
	s_nop 1
	v_cndmask_b32_e64 v50, v51, v52, s[4:5]
	v_mul_f32_e32 v51, 0x37800000, v50
	v_cndmask_b32_e32 v50, v50, v51, vcc
	v_cmp_class_f32_e32 vcc, v44, v244
	s_nop 1
	v_cndmask_b32_e32 v44, v50, v44, vcc
	v_div_scale_f32 v50, s[4:5], v44, v44, 1.0
	v_rcp_f32_e32 v51, v50
	s_nop 0
	v_fma_f32 v52, -v50, v51, 1.0
	v_fmac_f32_e32 v51, v52, v51
	v_div_scale_f32 v52, vcc, 1.0, v44, 1.0
	v_mul_f32_e32 v53, v52, v51
	v_fma_f32 v54, -v50, v53, v52
	v_fmac_f32_e32 v53, v54, v51
	v_fma_f32 v50, -v50, v53, v52
	v_div_fmas_f32 v50, v50, v51, v53
	v_div_fixup_f32 v44, v50, v44, 1.0
	v_mov_b64_e32 v[50:51], v[96:97]
	v_mov_b64_e32 v[52:53], v[98:99]
	v_pk_mul_f32 v[26:27], v[26:27], v[44:45] op_sel_hi:[1,0]
	v_pk_mul_f32 v[24:25], v[24:25], v[44:45] op_sel_hi:[1,0]
	v_pk_mul_f32 v[16:17], v[16:17], v[44:45] op_sel_hi:[1,0]
	v_pk_mul_f32 v[18:19], v[18:19], v[44:45] op_sel_hi:[1,0]
	v_pk_mul_f32 v[8:9], v[8:9], v[44:45] op_sel_hi:[1,0]
	v_pk_mul_f32 v[10:11], v[10:11], v[44:45] op_sel_hi:[1,0]
	v_pk_mul_f32 v[0:1], v[0:1], v[44:45] op_sel_hi:[1,0]
	v_pk_mul_f32 v[2:3], v[2:3], v[44:45] op_sel_hi:[1,0]
	v_pk_mul_f32 v[28:29], v[50:51], v[28:29]
	v_pk_mul_f32 v[30:31], v[52:53], v[30:31]
	v_pk_mul_f32 v[52:53], v[52:53], v[26:27]
	v_bfe_u32 v26, v28, 16, 1
	v_add3_u32 v26, v28, v26, s33
	v_bfe_u32 v27, v29, 16, 1
	v_lshrrev_b32_e32 v26, 16, v26
	v_add3_u32 v27, v29, v27, s33
	v_and_or_b32 v26, v27, s37, v26
	v_bfe_u32 v27, v30, 16, 1
	v_add3_u32 v27, v30, v27, s33
	v_bfe_u32 v28, v31, 16, 1
	v_lshrrev_b32_e32 v27, 16, v27
	v_add3_u32 v28, v31, v28, s33
	v_pk_mul_f32 v[24:25], v[50:51], v[24:25]
	v_and_or_b32 v27, v28, s37, v27
	global_store_dwordx2 v[38:39], v[26:27], off
	v_bfe_u32 v26, v24, 16, 1
	v_add3_u32 v24, v24, v26, s33
	v_bfe_u32 v26, v25, 16, 1
	v_lshrrev_b32_e32 v24, 16, v24
	v_add3_u32 v25, v25, v26, s33
	v_and_or_b32 v26, v25, s37, v24
	v_bfe_u32 v24, v52, 16, 1
	v_add3_u32 v24, v52, v24, s33
	v_bfe_u32 v25, v53, 16, 1
	v_lshrrev_b32_e32 v24, 16, v24
	v_add3_u32 v25, v53, v25, s33
	v_and_or_b32 v27, v25, s37, v24
	v_lshl_add_u64 v[24:25], v[36:37], 0, s[0:1]
	global_store_dwordx2 v[24:25], v[26:27], off
	v_mov_b64_e32 v[26:27], v[100:101]
	v_mov_b64_e32 v[28:29], v[102:103]
	v_pk_mul_f32 v[20:21], v[26:27], v[20:21]
	v_pk_mul_f32 v[16:17], v[26:27], v[16:17]
	v_bfe_u32 v26, v20, 16, 1
	v_add3_u32 v20, v20, v26, s33
	v_bfe_u32 v26, v21, 16, 1
	v_pk_mul_f32 v[22:23], v[28:29], v[22:23]
	v_lshrrev_b32_e32 v20, 16, v20
	v_add3_u32 v21, v21, v26, s33
	v_and_or_b32 v20, v21, s37, v20
	v_bfe_u32 v21, v22, 16, 1
	v_add3_u32 v21, v22, v21, s33
	v_bfe_u32 v22, v23, 16, 1
	v_lshrrev_b32_e32 v21, 16, v21
	v_add3_u32 v22, v23, v22, s33
	v_and_or_b32 v21, v22, s37, v21
	global_store_dwordx2 v[38:39], v[20:21], off offset:512
	v_bfe_u32 v20, v16, 16, 1
	v_add3_u32 v16, v16, v20, s33
	v_bfe_u32 v20, v17, 16, 1
	v_pk_mul_f32 v[18:19], v[28:29], v[18:19]
	v_lshrrev_b32_e32 v16, 16, v16
	v_add3_u32 v17, v17, v20, s33
	v_and_or_b32 v16, v17, s37, v16
	v_bfe_u32 v17, v18, 16, 1
	v_add3_u32 v17, v18, v17, s33
	v_bfe_u32 v18, v19, 16, 1
	v_lshrrev_b32_e32 v17, 16, v17
	v_add3_u32 v18, v19, v18, s33
	v_and_or_b32 v17, v18, s37, v17
	global_store_dwordx2 v[24:25], v[16:17], off offset:512
	v_mov_b64_e32 v[16:17], v[104:105]
	v_mov_b64_e32 v[18:19], v[106:107]
	v_pk_mul_f32 v[12:13], v[12:13], v[16:17]
	v_pk_mul_f32 v[8:9], v[16:17], v[8:9]
	v_bfe_u32 v16, v12, 16, 1
	v_add3_u32 v12, v12, v16, s33
	v_bfe_u32 v16, v13, 16, 1
	v_pk_mul_f32 v[14:15], v[14:15], v[18:19]
	v_lshrrev_b32_e32 v12, 16, v12
	v_add3_u32 v13, v13, v16, s33
	v_and_or_b32 v12, v13, s37, v12
	v_bfe_u32 v13, v14, 16, 1
	v_add3_u32 v13, v14, v13, s33
	v_bfe_u32 v14, v15, 16, 1
	v_lshrrev_b32_e32 v13, 16, v13
	v_add3_u32 v14, v15, v14, s33
	v_and_or_b32 v13, v14, s37, v13
	global_store_dwordx2 v[38:39], v[12:13], off offset:1024
	v_bfe_u32 v12, v8, 16, 1
	v_add3_u32 v8, v8, v12, s33
	v_bfe_u32 v12, v9, 16, 1
	v_pk_mul_f32 v[10:11], v[18:19], v[10:11]
	v_lshrrev_b32_e32 v8, 16, v8
	v_add3_u32 v9, v9, v12, s33
	v_and_or_b32 v8, v9, s37, v8
	v_bfe_u32 v9, v10, 16, 1
	v_add3_u32 v9, v10, v9, s33
	v_bfe_u32 v10, v11, 16, 1
	v_lshrrev_b32_e32 v9, 16, v9
	v_add3_u32 v10, v11, v10, s33
	v_and_or_b32 v9, v10, s37, v9
	global_store_dwordx2 v[24:25], v[8:9], off offset:1024
	v_mov_b64_e32 v[8:9], v[108:109]
	v_mov_b64_e32 v[10:11], v[110:111]
	v_pk_mul_f32 v[4:5], v[4:5], v[8:9]
	v_pk_mul_f32 v[0:1], v[0:1], v[8:9]
	v_bfe_u32 v8, v4, 16, 1
	v_add3_u32 v4, v4, v8, s33
	v_bfe_u32 v8, v5, 16, 1
	v_pk_mul_f32 v[6:7], v[6:7], v[10:11]
	v_lshrrev_b32_e32 v4, 16, v4
	v_add3_u32 v5, v5, v8, s33
	v_and_or_b32 v4, v5, s37, v4
	v_bfe_u32 v5, v6, 16, 1
	v_add3_u32 v5, v6, v5, s33
	v_bfe_u32 v6, v7, 16, 1
	v_lshrrev_b32_e32 v5, 16, v5
	v_add3_u32 v6, v7, v6, s33
	v_and_or_b32 v5, v6, s37, v5
	global_store_dwordx2 v[38:39], v[4:5], off offset:1536
	v_bfe_u32 v4, v0, 16, 1
	v_add3_u32 v0, v0, v4, s33
	v_bfe_u32 v4, v1, 16, 1
	v_pk_mul_f32 v[2:3], v[2:3], v[10:11]
	v_lshrrev_b32_e32 v0, 16, v0
	v_add3_u32 v1, v1, v4, s33
	v_and_or_b32 v0, v1, s37, v0
	v_bfe_u32 v1, v2, 16, 1
	v_add3_u32 v1, v2, v1, s33
	v_bfe_u32 v2, v3, 16, 1
	v_lshrrev_b32_e32 v1, 16, v1
	v_add3_u32 v2, v3, v2, s33
	v_and_or_b32 v1, v2, s37, v1
	v_lshl_add_u64 v[38:39], v[38:39], 0, s[34:35]
	global_store_dwordx2 v[24:25], v[0:1], off offset:1536
	s_cbranch_scc0 .LBB0_276

; #define OPQV(v) asm volatile("" : "+v"(v) :: "memory")
; __global__ void __launch_bounds__(NWAVES * 64, 2) fwd_megakernel(Params P) {
;     ...
;         lno = (int)threadIdx.x; OPQV(lno); lno &= 63; for (int m = gw; m < MTOK; m += 2 * ngw) { const int m1 = (m + ngw < MTOK) ? m + ngw : m; rms_row2(X + (size_t)m * DM, X + (size_t)m1 * DM, P.in[18] + l * DM, XN + (size_t)m * DM, XN + (size_t)m1 * DM, nullptr, nullptr, lno); }
.LBB0_856:
	s_or_b64 exec, exec, s[0:1]
	s_waitcnt lgkmcnt(0)
	v_mov_b32_e32 v0, v236
	s_barrier
	v_readlane_b32 s0, v255, 25
	v_readlane_b32 s1, v255, 26
	v_readlane_b32 s14, v254, 31
	s_and_b64 vcc, exec, s[0:1]
	v_readlane_b32 s8, v254, 29
	v_readlane_b32 s15, v254, 32
	s_mov_b32 s7, 0xf800000
	v_readlane_b32 s9, v254, 30
	s_cbranch_vccnz .LBB0_859
	v_readlane_b32 s0, v254, 52
	v_readlane_b32 s1, v254, 53
	s_lshl_b32 s26, s0, 10
	v_readlane_b32 s20, v254, 56
	s_lshl_b64 s[0:1], s[26:27], 2
	v_readlane_b32 s22, v254, 58
	v_and_b32_e32 v0, 63, v0
	v_readlane_b32 s23, v254, 59
	s_add_u32 s0, s22, s0
	s_addc_u32 s1, s23, s1
	v_lshlrev_b32_e32 v208, 4, v0
	v_lshl_add_u64 v[34:35], s[0:1], 0, v[208:209]
	v_lshlrev_b32_e32 v1, 2, v0
	v_readlane_b32 s0, v252, 2
	v_xor_b32_e32 v43, 4, v1
	v_xor_b32_e32 v45, 8, v1
	v_xor_b32_e32 v46, 16, v1
	v_xor_b32_e32 v47, 32, v1
	v_xor_b32_e32 v48, 64, v1
	v_xor_b32_e32 v49, 0x80, v1
	v_lshlrev_b32_e32 v0, 3, v0
	v_mov_b32_e32 v1, v209
	v_readlane_b32 s1, v252, 3
	v_lshl_add_u64 v[32:33], s[68:69], 0, v[208:209]
	v_readlane_b32 s21, v254, 57
	v_lshl_add_u64 v[36:37], s[0:1], 0, v[0:1]
	v_readlane_b32 s0, v254, 25
	v_readlane_b32 s1, v254, 26
	s_nop 1
	v_lshl_add_u64 v[38:39], s[0:1], 0, v[0:1]
	v_readlane_b32 s0, v254, 35
	v_readlane_b32 s1, v254, 36
	s_nop 1
	v_lshl_add_u64 v[40:41], s[0:1], 0, v[208:209]
	v_readlane_b32 s0, v254, 27
	s_mov_b32 s6, s0
	v_readlane_b32 s1, v254, 28
	global_load_dwordx4 v[96:99], v[34:35], off
	global_load_dwordx4 v[100:103], v[34:35], off offset:1024
	global_load_dwordx4 v[104:107], v[34:35], off offset:2048
	global_load_dwordx4 v[108:111], v[34:35], off offset:3072
	s_waitcnt vmcnt(0)
